# v5 stack plus: any-score test on partial maxima, final-norm 4-row batching with DPP sums, GEMM1 pre-load wait removal, retention epilogue DPP row sums
# speedup vs baseline: 1.0098x; 1.0042x over previous
.LBB0_33:
	v_mov_b32_e32 v12, 0
	v_mov_b32_e32 v13, 0
	v_mov_b32_e32 v14, 0
	v_mov_b32_e32 v15, 0
	s_and_saveexec_b64 s[10:11], vcc
	v_lshl_add_u64 v[16:17], s[88:89], 0, v[8:9]
	global_load_dword v12, v[16:17], off
	global_load_dword v13, v[16:17], off offset:64
	global_load_dword v14, v[16:17], off offset:128
	global_load_dword v15, v[16:17], off offset:192
	s_or_b64 exec, exec, s[10:11]
	v_lshl_add_u64 v[16:17], s[88:89], 0, v[6:7]
	s_mov_b32 s0, 0x9200000
	v_add_co_u32_e64 v16, s[42:43], s0, v16
	s_nop 1
	v_addc_co_u32_e64 v17, s[42:43], 0, v17, s[42:43]
	v_lshl_add_u64 v[18:19], v[16:17], 0, s[82:83]
	global_load_dwordx2 v[40:41], v[16:17], off
	global_load_dwordx2 v[42:43], v[16:17], off offset:512
	global_load_dwordx2 v[44:45], v[16:17], off offset:1024
	global_load_dwordx2 v[46:47], v[16:17], off offset:1536
	global_load_dwordx2 v[48:49], v[16:17], off offset:2048
	global_load_dwordx2 v[50:51], v[16:17], off offset:2560
	global_load_dwordx2 v[52:53], v[16:17], off offset:3072
	global_load_dwordx2 v[54:55], v[16:17], off offset:3584
	global_load_dwordx2 v[56:57], v[18:19], off
	global_load_dwordx2 v[58:59], v[18:19], off offset:512
	global_load_dwordx2 v[60:61], v[18:19], off offset:1024
	global_load_dwordx2 v[62:63], v[18:19], off offset:1536
	global_load_dwordx2 v[64:65], v[18:19], off offset:2048
	global_load_dwordx2 v[66:67], v[18:19], off offset:2560
	global_load_dwordx2 v[68:69], v[18:19], off offset:3072
	global_load_dwordx2 v[70:71], v[18:19], off offset:3584
	global_load_dwordx4 v[72:75], v[10:11], off
	global_load_dwordx4 v[76:79], v[10:11], off offset:1024
	global_load_dwordx4 v[80:83], v[10:11], off offset:2048
	global_load_dwordx4 v[84:87], v[10:11], off offset:3072
	s_waitcnt vmcnt(20)
	v_add_f32_dpp v12, v12, v12 quad_perm:[1,0,3,2] row_mask:0xf bank_mask:0xf
	v_add_f32_dpp v13, v13, v13 quad_perm:[1,0,3,2] row_mask:0xf bank_mask:0xf
	v_add_f32_dpp v14, v14, v14 quad_perm:[1,0,3,2] row_mask:0xf bank_mask:0xf
	v_add_f32_dpp v15, v15, v15 quad_perm:[1,0,3,2] row_mask:0xf bank_mask:0xf
	v_add_f32_dpp v12, v12, v12 quad_perm:[2,3,0,1] row_mask:0xf bank_mask:0xf
	v_add_f32_dpp v13, v13, v13 quad_perm:[2,3,0,1] row_mask:0xf bank_mask:0xf
	v_add_f32_dpp v14, v14, v14 quad_perm:[2,3,0,1] row_mask:0xf bank_mask:0xf
	v_add_f32_dpp v15, v15, v15 quad_perm:[2,3,0,1] row_mask:0xf bank_mask:0xf
	v_add_f32_dpp v12, v12, v12 row_half_mirror row_mask:0xf bank_mask:0xf
	v_add_f32_dpp v13, v13, v13 row_half_mirror row_mask:0xf bank_mask:0xf
	v_add_f32_dpp v14, v14, v14 row_half_mirror row_mask:0xf bank_mask:0xf
	v_add_f32_dpp v15, v15, v15 row_half_mirror row_mask:0xf bank_mask:0xf
	v_add_f32_dpp v12, v12, v12 row_mirror row_mask:0xf bank_mask:0xf
	v_add_f32_dpp v13, v13, v13 row_mirror row_mask:0xf bank_mask:0xf
	v_add_f32_dpp v14, v14, v14 row_mirror row_mask:0xf bank_mask:0xf
	v_add_f32_dpp v15, v15, v15 row_mirror row_mask:0xf bank_mask:0xf
	s_nop 1
	v_readlane_b32 s40, v12, 0
	v_readlane_b32 s41, v13, 0
	v_readlane_b32 s42, v14, 0
	v_readlane_b32 s43, v15, 0
	s_nop 1
	v_mov_b32_e32 v12, s40
	v_mov_b32_e32 v13, s41
	v_mov_b32_e32 v14, s42
	v_mov_b32_e32 v15, s43
	v_fmamk_f32 v12, v12, 0x3a800000, v180
	v_cmp_gt_f32_e64 s[40:41], s53, v12
	v_mul_f32_e32 v88, 0x4b800000, v12
	s_nop 0
	v_cndmask_b32_e64 v12, v12, v88, s[40:41]
	v_rsq_f32_e32 v36, v12
	s_nop 0
	v_mul_f32_e32 v88, 0x45800000, v36
	v_cndmask_b32_e64 v36, v36, v88, s[40:41]
	v_fmamk_f32 v13, v13, 0x3a800000, v180
	v_cmp_gt_f32_e64 s[40:41], s53, v13
	v_mul_f32_e32 v88, 0x4b800000, v13
	s_nop 0
	v_cndmask_b32_e64 v13, v13, v88, s[40:41]
	v_rsq_f32_e32 v38, v13
	s_nop 0
	v_mul_f32_e32 v88, 0x45800000, v38
	v_cndmask_b32_e64 v38, v38, v88, s[40:41]
	v_fmamk_f32 v14, v14, 0x3a800000, v180
	v_cmp_gt_f32_e64 s[40:41], s53, v14
	v_mul_f32_e32 v88, 0x4b800000, v14
	s_nop 0
	v_cndmask_b32_e64 v14, v14, v88, s[40:41]
	v_rsq_f32_e32 v96, v14
	s_nop 0
	v_mul_f32_e32 v88, 0x45800000, v96
	v_cndmask_b32_e64 v96, v96, v88, s[40:41]
	v_fmamk_f32 v15, v15, 0x3a800000, v180
	v_cmp_gt_f32_e64 s[40:41], s53, v15
	v_mul_f32_e32 v88, 0x4b800000, v15
	s_nop 0
	v_cndmask_b32_e64 v15, v15, v88, s[40:41]
	v_rsq_f32_e32 v98, v15
	s_nop 0
	v_mul_f32_e32 v88, 0x45800000, v98
	v_cndmask_b32_e64 v98, v98, v88, s[40:41]
	v_lshl_add_u64 v[100:101], v[0:1], 2, s[12:13]
	s_waitcnt vmcnt(0)
	v_lshlrev_b32_e32 v88, 16, v40
	v_and_b32_e32 v89, 0xffff0000, v40
	v_lshlrev_b32_e32 v90, 16, v41
	v_and_b32_e32 v91, 0xffff0000, v41
	v_pk_mul_f32 v[88:89], v[72:73], v[88:89]
	v_pk_mul_f32 v[90:91], v[74:75], v[90:91]
	v_pk_mul_f32 v[88:89], v[88:89], v[36:37] op_sel_hi:[1,0]
	v_pk_mul_f32 v[90:91], v[90:91], v[36:37] op_sel_hi:[1,0]
	global_store_dwordx4 v[100:101], v[88:91], off sc1
	s_nop 1
	v_lshlrev_b32_e32 v92, 16, v42
	v_and_b32_e32 v93, 0xffff0000, v42
	v_lshlrev_b32_e32 v94, 16, v43
	v_and_b32_e32 v95, 0xffff0000, v43
	v_pk_mul_f32 v[92:93], v[76:77], v[92:93]
	v_pk_mul_f32 v[94:95], v[78:79], v[94:95]
	v_pk_mul_f32 v[92:93], v[92:93], v[36:37] op_sel_hi:[1,0]
	v_pk_mul_f32 v[94:95], v[94:95], v[36:37] op_sel_hi:[1,0]
	global_store_dwordx4 v[100:101], v[92:95], off offset:1024 sc1
	s_nop 1
	v_lshlrev_b32_e32 v88, 16, v44
	v_and_b32_e32 v89, 0xffff0000, v44
	v_lshlrev_b32_e32 v90, 16, v45
	v_and_b32_e32 v91, 0xffff0000, v45
	v_pk_mul_f32 v[88:89], v[80:81], v[88:89]
	v_pk_mul_f32 v[90:91], v[82:83], v[90:91]
	v_pk_mul_f32 v[88:89], v[88:89], v[36:37] op_sel_hi:[1,0]
	v_pk_mul_f32 v[90:91], v[90:91], v[36:37] op_sel_hi:[1,0]
	global_store_dwordx4 v[100:101], v[88:91], off offset:2048 sc1
	s_nop 1
	v_lshlrev_b32_e32 v92, 16, v46
	v_and_b32_e32 v93, 0xffff0000, v46
	v_lshlrev_b32_e32 v94, 16, v47
	v_and_b32_e32 v95, 0xffff0000, v47
	v_pk_mul_f32 v[92:93], v[84:85], v[92:93]
	v_pk_mul_f32 v[94:95], v[86:87], v[94:95]
	v_pk_mul_f32 v[92:93], v[92:93], v[36:37] op_sel_hi:[1,0]
	v_pk_mul_f32 v[94:95], v[94:95], v[36:37] op_sel_hi:[1,0]
	global_store_dwordx4 v[100:101], v[92:95], off offset:3072 sc1
	s_nop 1
	v_lshl_add_u64 v[100:101], v[100:101], 0, s[82:83]
	v_lshlrev_b32_e32 v88, 16, v48
	v_and_b32_e32 v89, 0xffff0000, v48
	v_lshlrev_b32_e32 v90, 16, v49
	v_and_b32_e32 v91, 0xffff0000, v49
	v_pk_mul_f32 v[88:89], v[72:73], v[88:89]
	v_pk_mul_f32 v[90:91], v[74:75], v[90:91]
	v_pk_mul_f32 v[88:89], v[88:89], v[38:39] op_sel_hi:[1,0]
	v_pk_mul_f32 v[90:91], v[90:91], v[38:39] op_sel_hi:[1,0]
	global_store_dwordx4 v[100:101], v[88:91], off sc1
	s_nop 1
	v_lshlrev_b32_e32 v92, 16, v50
	v_and_b32_e32 v93, 0xffff0000, v50
	v_lshlrev_b32_e32 v94, 16, v51
	v_and_b32_e32 v95, 0xffff0000, v51
	v_pk_mul_f32 v[92:93], v[76:77], v[92:93]
	v_pk_mul_f32 v[94:95], v[78:79], v[94:95]
	v_pk_mul_f32 v[92:93], v[92:93], v[38:39] op_sel_hi:[1,0]
	v_pk_mul_f32 v[94:95], v[94:95], v[38:39] op_sel_hi:[1,0]
	global_store_dwordx4 v[100:101], v[92:95], off offset:1024 sc1
	s_nop 1
	v_lshlrev_b32_e32 v88, 16, v52
	v_and_b32_e32 v89, 0xffff0000, v52
	v_lshlrev_b32_e32 v90, 16, v53
	v_and_b32_e32 v91, 0xffff0000, v53
	v_pk_mul_f32 v[88:89], v[80:81], v[88:89]
	v_pk_mul_f32 v[90:91], v[82:83], v[90:91]
	v_pk_mul_f32 v[88:89], v[88:89], v[38:39] op_sel_hi:[1,0]
	v_pk_mul_f32 v[90:91], v[90:91], v[38:39] op_sel_hi:[1,0]
	global_store_dwordx4 v[100:101], v[88:91], off offset:2048 sc1
	s_nop 1
	v_lshlrev_b32_e32 v92, 16, v54
	v_and_b32_e32 v93, 0xffff0000, v54
	v_lshlrev_b32_e32 v94, 16, v55
	v_and_b32_e32 v95, 0xffff0000, v55
	v_pk_mul_f32 v[92:93], v[84:85], v[92:93]
	v_pk_mul_f32 v[94:95], v[86:87], v[94:95]
	v_pk_mul_f32 v[92:93], v[92:93], v[38:39] op_sel_hi:[1,0]
	v_pk_mul_f32 v[94:95], v[94:95], v[38:39] op_sel_hi:[1,0]
	global_store_dwordx4 v[100:101], v[92:95], off offset:3072 sc1
	s_nop 1
	v_lshl_add_u64 v[100:101], v[100:101], 0, s[82:83]
	v_lshlrev_b32_e32 v88, 16, v56
	v_and_b32_e32 v89, 0xffff0000, v56
	v_lshlrev_b32_e32 v90, 16, v57
	v_and_b32_e32 v91, 0xffff0000, v57
	v_pk_mul_f32 v[88:89], v[72:73], v[88:89]
	v_pk_mul_f32 v[90:91], v[74:75], v[90:91]
	v_pk_mul_f32 v[88:89], v[88:89], v[96:97] op_sel_hi:[1,0]
	v_pk_mul_f32 v[90:91], v[90:91], v[96:97] op_sel_hi:[1,0]
	global_store_dwordx4 v[100:101], v[88:91], off sc1
	s_nop 1
	v_lshlrev_b32_e32 v92, 16, v58
	v_and_b32_e32 v93, 0xffff0000, v58
	v_lshlrev_b32_e32 v94, 16, v59
	v_and_b32_e32 v95, 0xffff0000, v59
	v_pk_mul_f32 v[92:93], v[76:77], v[92:93]
	v_pk_mul_f32 v[94:95], v[78:79], v[94:95]
	v_pk_mul_f32 v[92:93], v[92:93], v[96:97] op_sel_hi:[1,0]
	v_pk_mul_f32 v[94:95], v[94:95], v[96:97] op_sel_hi:[1,0]
	global_store_dwordx4 v[100:101], v[92:95], off offset:1024 sc1
	s_nop 1
	v_lshlrev_b32_e32 v88, 16, v60
	v_and_b32_e32 v89, 0xffff0000, v60
	v_lshlrev_b32_e32 v90, 16, v61
	v_and_b32_e32 v91, 0xffff0000, v61
	v_pk_mul_f32 v[88:89], v[80:81], v[88:89]
	v_pk_mul_f32 v[90:91], v[82:83], v[90:91]
	v_pk_mul_f32 v[88:89], v[88:89], v[96:97] op_sel_hi:[1,0]
	v_pk_mul_f32 v[90:91], v[90:91], v[96:97] op_sel_hi:[1,0]
	global_store_dwordx4 v[100:101], v[88:91], off offset:2048 sc1
	s_nop 1
	v_lshlrev_b32_e32 v92, 16, v62
	v_and_b32_e32 v93, 0xffff0000, v62
	v_lshlrev_b32_e32 v94, 16, v63
	v_and_b32_e32 v95, 0xffff0000, v63
	v_pk_mul_f32 v[92:93], v[84:85], v[92:93]
	v_pk_mul_f32 v[94:95], v[86:87], v[94:95]
	v_pk_mul_f32 v[92:93], v[92:93], v[96:97] op_sel_hi:[1,0]
	v_pk_mul_f32 v[94:95], v[94:95], v[96:97] op_sel_hi:[1,0]
	global_store_dwordx4 v[100:101], v[92:95], off offset:3072 sc1
	s_nop 1
	v_lshl_add_u64 v[100:101], v[100:101], 0, s[82:83]
	v_lshlrev_b32_e32 v88, 16, v64
	v_and_b32_e32 v89, 0xffff0000, v64
	v_lshlrev_b32_e32 v90, 16, v65
	v_and_b32_e32 v91, 0xffff0000, v65
	v_pk_mul_f32 v[88:89], v[72:73], v[88:89]
	v_pk_mul_f32 v[90:91], v[74:75], v[90:91]
	v_pk_mul_f32 v[88:89], v[88:89], v[98:99] op_sel_hi:[1,0]
	v_pk_mul_f32 v[90:91], v[90:91], v[98:99] op_sel_hi:[1,0]
	global_store_dwordx4 v[100:101], v[88:91], off sc1
	s_nop 1
	v_lshlrev_b32_e32 v92, 16, v66
	v_and_b32_e32 v93, 0xffff0000, v66
	v_lshlrev_b32_e32 v94, 16, v67
	v_and_b32_e32 v95, 0xffff0000, v67
	v_pk_mul_f32 v[92:93], v[76:77], v[92:93]
	v_pk_mul_f32 v[94:95], v[78:79], v[94:95]
	v_pk_mul_f32 v[92:93], v[92:93], v[98:99] op_sel_hi:[1,0]
	v_pk_mul_f32 v[94:95], v[94:95], v[98:99] op_sel_hi:[1,0]
	global_store_dwordx4 v[100:101], v[92:95], off offset:1024 sc1
	s_nop 1
	v_lshlrev_b32_e32 v88, 16, v68
	v_and_b32_e32 v89, 0xffff0000, v68
	v_lshlrev_b32_e32 v90, 16, v69
	v_and_b32_e32 v91, 0xffff0000, v69
	v_pk_mul_f32 v[88:89], v[80:81], v[88:89]
	v_pk_mul_f32 v[90:91], v[82:83], v[90:91]
	v_pk_mul_f32 v[88:89], v[88:89], v[98:99] op_sel_hi:[1,0]
	v_pk_mul_f32 v[90:91], v[90:91], v[98:99] op_sel_hi:[1,0]
	global_store_dwordx4 v[100:101], v[88:91], off offset:2048 sc1
	s_nop 1
	v_lshlrev_b32_e32 v92, 16, v70
	v_and_b32_e32 v93, 0xffff0000, v70
	v_lshlrev_b32_e32 v94, 16, v71
	v_and_b32_e32 v95, 0xffff0000, v71
	v_pk_mul_f32 v[92:93], v[84:85], v[92:93]
	v_pk_mul_f32 v[94:95], v[86:87], v[94:95]
	v_pk_mul_f32 v[92:93], v[92:93], v[98:99] op_sel_hi:[1,0]
	v_pk_mul_f32 v[94:95], v[94:95], v[98:99] op_sel_hi:[1,0]
	global_store_dwordx4 v[100:101], v[92:95], off offset:3072 sc1
	s_nop 1
	s_branch .LBB0_17

.LBB0_264:
	s_or_b64 exec, exec, s[56:57]
	s_lshl_b64 s[36:37], s[52:53], 2
	s_add_u32 s64, s39, s36
	s_addc_u32 s65, s8, s37
	v_ashrrev_i32_e32 v56, 3, v80
	s_add_i32 s0, s40, s51
	s_lshl_b32 s60, s2, 1
	v_lshlrev_b32_e32 v33, 3, v80
	v_add_u32_e32 v32, s0, v56
	s_add_u32 s2, s18, s60
	v_and_b32_e32 v57, 56, v33
	s_addc_u32 s3, s19, 0
	v_lshlrev_b32_e32 v80, 1, v57
	v_ashrrev_i32_e32 v33, 31, v32
	v_add_u32_e32 v38, 8, v32
	v_lshl_add_u64 v[34:35], s[2:3], 0, v[80:81]
	v_lshlrev_b64 v[52:53], 11, v[32:33]
	v_ashrrev_i32_e32 v39, 31, v38
	v_lshl_add_u64 v[36:37], v[34:35], 0, v[52:53]
	v_lshlrev_b64 v[54:55], 11, v[38:39]
	s_waitcnt lgkmcnt(0)
	s_barrier
	v_lshl_add_u64 v[38:39], v[34:35], 0, v[54:55]
	global_load_dwordx4 v[40:43], v[36:37], off
	global_load_dwordx4 v[44:47], v[38:39], off
	v_add_u32_e32 v36, 16, v32
	v_add_u32_e32 v32, 24, v32
	v_ashrrev_i32_e32 v37, 31, v36
	v_ashrrev_i32_e32 v33, 31, v32
	s_movk_i32 s0, 0x440
	v_lshlrev_b64 v[38:39], 11, v[36:37]
	v_lshlrev_b64 v[36:37], 11, v[32:33]
	v_lshlrev_b32_e32 v58, 2, v114
	v_mul_lo_u32 v59, v136, s0
	v_lshl_add_u64 v[48:49], v[34:35], 0, v[38:39]
	v_lshl_add_u64 v[32:33], v[34:35], 0, v[36:37]
	v_add3_u32 v58, s9, v58, v59
	global_load_dwordx4 v[48:51], v[48:49], off
	s_nop 0
	global_load_dwordx4 v[32:35], v[32:33], off
	ds_write2_b32 v58, v16, v0 offset1:32
	ds_write2_b32 v58, v17, v1 offset0:68 offset1:100
	ds_write2_b32 v58, v18, v2 offset0:136 offset1:168
	ds_write2_b32 v58, v19, v3 offset0:204 offset1:236
	v_add_u32_e32 v0, 0x800, v58
	ds_write2_b32 v0, v20, v4 offset0:32 offset1:64
	ds_write2_b32 v0, v21, v5 offset0:100 offset1:132
	ds_write2_b32 v0, v22, v6 offset0:168 offset1:200
	v_add_u32_e32 v0, 0xa00, v58
	ds_write2_b32 v0, v23, v7 offset0:108 offset1:140
	v_add_u32_e32 v0, 0x1000, v58
	ds_write2_b32 v0, v24, v8 offset0:64 offset1:96
	ds_write2_b32 v0, v25, v9 offset0:132 offset1:164
	ds_write2_b32 v0, v26, v10 offset0:200 offset1:232
	v_add_u32_e32 v0, 0x1400, v58
	ds_write2_b32 v0, v27, v11 offset0:12 offset1:44
	v_add_u32_e32 v0, 0x1800, v58
	ds_write2_b32 v0, v28, v12 offset0:96 offset1:128
	ds_write2_b32 v0, v29, v13 offset0:164 offset1:196
	v_add_u32_e32 v0, 0x1a00, v58
	ds_write2_b32 v0, v30, v14 offset0:104 offset1:136
	v_add_u32_e32 v0, 0x1c00, v58
	ds_write2_b32 v0, v31, v15 offset0:44 offset1:76
	v_lshlrev_b32_e32 v0, 2, v57
	v_mul_lo_u32 v1, v56, s77
	v_add3_u32 v16, s9, v0, v1
	s_waitcnt lgkmcnt(0)
	ds_read_b128 v[0:3], v16
	ds_read_b128 v[4:7], v16 offset:16
	s_mov_b64 s[40:41], s[42:43]
	s_waitcnt lgkmcnt(0)
	v_pk_mul_f32 v[8:9], v[2:3], v[2:3]
	v_pk_mul_f32 v[10:11], v[0:1], v[0:1]
	s_nop 0
	v_pk_mov_b32 v[12:13], v[10:11], v[8:9] op_sel:[1,0]
	v_mov_b32_e32 v11, v9
	v_pk_add_f32 v[8:9], v[12:13], v[10:11]
	v_pk_mul_f32 v[10:11], v[6:7], v[6:7]
	v_pk_mul_f32 v[12:13], v[4:5], v[4:5]
	v_mov_b32_e32 v14, v10
	v_mov_b32_e32 v15, v12
	v_mov_b32_e32 v12, v11
	v_pk_add_f32 v[10:11], v[14:15], v[12:13]
	v_add_f32_e32 v8, v8, v9
	v_add_f32_e32 v8, v8, v11
	v_add_f32_e32 v8, v10, v8
	s_nop 1
	v_add_f32_dpp v8, v8, v8 quad_perm:[1,0,3,2] row_mask:0xf bank_mask:0xf
	s_nop 1
	v_add_f32_dpp v8, v8, v8 quad_perm:[2,3,0,1] row_mask:0xf bank_mask:0xf
	s_nop 1
	v_add_f32_dpp v8, v8, v8 row_half_mirror row_mask:0xf bank_mask:0xf
	v_fmamk_f32 v8, v8, 0x3c800000, v180
	v_mul_f32_e32 v9, 0x4b800000, v8
	v_cmp_gt_f32_e32 vcc, s1, v8
	s_waitcnt vmcnt(0)
	v_lshlrev_b32_e32 v10, 16, v40
	v_cndmask_b32_e32 v8, v8, v9, vcc
	v_rsq_f32_e32 v8, v8
	v_and_b32_e32 v11, 0xffff0000, v40
	v_mul_f32_e32 v9, 0x45800000, v8
	v_cndmask_b32_e32 v8, v8, v9, vcc
	v_pk_mul_f32 v[0:1], v[0:1], v[8:9] op_sel_hi:[1,0]
	v_pk_mul_f32 v[2:3], v[2:3], v[8:9] op_sel_hi:[1,0]
	v_pk_mul_f32 v[0:1], v[0:1], v[10:11]
	v_lshlrev_b32_e32 v10, 16, v41
	v_and_b32_e32 v11, 0xffff0000, v41
	v_pk_mul_f32 v[2:3], v[2:3], v[10:11]
	v_cvt_pk_bf16_f32 v0, v0, v1
	v_cvt_pk_bf16_f32 v1, v2, v3
	v_pk_mul_f32 v[2:3], v[4:5], v[8:9] op_sel_hi:[1,0]
	v_lshlrev_b32_e32 v4, 16, v42
	v_and_b32_e32 v5, 0xffff0000, v42
	v_pk_mul_f32 v[2:3], v[2:3], v[4:5]
	v_pk_mul_f32 v[4:5], v[6:7], v[8:9] op_sel_hi:[1,0]
	v_lshlrev_b32_e32 v6, 16, v43
	v_and_b32_e32 v7, 0xffff0000, v43
	v_pk_mul_f32 v[4:5], v[4:5], v[6:7]
	v_cvt_pk_bf16_f32 v2, v2, v3
	v_cvt_pk_bf16_f32 v3, v4, v5
	v_lshl_add_u64 v[4:5], s[26:27], 0, v[52:53]
	v_lshl_add_u64 v[4:5], v[4:5], 0, s[60:61]
	v_lshl_add_u64 v[4:5], v[4:5], 0, v[80:81]
	global_store_dwordx4 v[4:5], v[0:3], off sc1
	s_nop 1
	ds_read_b128 v[0:3], v16 offset:2176
	ds_read_b128 v[4:7], v16 offset:2192
	s_waitcnt lgkmcnt(1)
	v_pk_mul_f32 v[8:9], v[2:3], v[2:3]
	v_pk_mul_f32 v[10:11], v[0:1], v[0:1]
	s_nop 0
	v_pk_mov_b32 v[12:13], v[10:11], v[8:9] op_sel:[1,0]
	v_mov_b32_e32 v11, v9
	v_pk_add_f32 v[8:9], v[12:13], v[10:11]
	s_waitcnt lgkmcnt(0)
	v_pk_mul_f32 v[10:11], v[6:7], v[6:7]
	v_pk_mul_f32 v[12:13], v[4:5], v[4:5]
	v_mov_b32_e32 v14, v10
	v_mov_b32_e32 v15, v12
	v_mov_b32_e32 v12, v11
	v_pk_add_f32 v[10:11], v[14:15], v[12:13]
	v_add_f32_e32 v8, v8, v9
	v_add_f32_e32 v8, v8, v11
	v_add_f32_e32 v8, v10, v8
	v_lshlrev_b32_e32 v10, 16, v44
	v_and_b32_e32 v11, 0xffff0000, v44
	s_nop 1
	v_add_f32_dpp v8, v8, v8 quad_perm:[1,0,3,2] row_mask:0xf bank_mask:0xf
	s_nop 1
	v_add_f32_dpp v8, v8, v8 quad_perm:[2,3,0,1] row_mask:0xf bank_mask:0xf
	s_nop 1
	v_add_f32_dpp v8, v8, v8 row_half_mirror row_mask:0xf bank_mask:0xf
	v_fmamk_f32 v8, v8, 0x3c800000, v180
	v_mul_f32_e32 v9, 0x4b800000, v8
	v_cmp_gt_f32_e32 vcc, s1, v8
	s_nop 1
	v_cndmask_b32_e32 v8, v8, v9, vcc
	v_rsq_f32_e32 v8, v8
	s_nop 0
	v_mul_f32_e32 v9, 0x45800000, v8
	v_cndmask_b32_e32 v8, v8, v9, vcc
	v_pk_mul_f32 v[0:1], v[0:1], v[8:9] op_sel_hi:[1,0]
	v_pk_mul_f32 v[2:3], v[2:3], v[8:9] op_sel_hi:[1,0]
	v_pk_mul_f32 v[0:1], v[0:1], v[10:11]
	v_lshlrev_b32_e32 v10, 16, v45
	v_and_b32_e32 v11, 0xffff0000, v45
	v_pk_mul_f32 v[2:3], v[2:3], v[10:11]
	v_cvt_pk_bf16_f32 v0, v0, v1
	v_cvt_pk_bf16_f32 v1, v2, v3
	v_pk_mul_f32 v[2:3], v[4:5], v[8:9] op_sel_hi:[1,0]
	v_lshlrev_b32_e32 v4, 16, v46
	v_and_b32_e32 v5, 0xffff0000, v46
	v_pk_mul_f32 v[2:3], v[2:3], v[4:5]
	v_pk_mul_f32 v[4:5], v[6:7], v[8:9] op_sel_hi:[1,0]
	v_lshlrev_b32_e32 v6, 16, v47
	v_and_b32_e32 v7, 0xffff0000, v47
	v_pk_mul_f32 v[4:5], v[4:5], v[6:7]
	v_cvt_pk_bf16_f32 v2, v2, v3
	v_cvt_pk_bf16_f32 v3, v4, v5
	v_lshl_add_u64 v[4:5], s[26:27], 0, v[54:55]
	v_lshl_add_u64 v[4:5], v[4:5], 0, s[60:61]
	v_lshl_add_u64 v[4:5], v[4:5], 0, v[80:81]
	global_store_dwordx4 v[4:5], v[0:3], off sc1
	s_nop 1
	ds_read_b128 v[0:3], v16 offset:4352
	ds_read_b128 v[4:7], v16 offset:4368
	s_waitcnt lgkmcnt(1)
	v_pk_mul_f32 v[8:9], v[2:3], v[2:3]
	v_pk_mul_f32 v[10:11], v[0:1], v[0:1]
	s_nop 0
	v_pk_mov_b32 v[12:13], v[10:11], v[8:9] op_sel:[1,0]
	v_mov_b32_e32 v11, v9
	v_pk_add_f32 v[8:9], v[12:13], v[10:11]
	s_waitcnt lgkmcnt(0)
	v_pk_mul_f32 v[10:11], v[6:7], v[6:7]
	v_pk_mul_f32 v[12:13], v[4:5], v[4:5]
	v_mov_b32_e32 v14, v10
	v_mov_b32_e32 v15, v12
	v_mov_b32_e32 v12, v11
	v_pk_add_f32 v[10:11], v[14:15], v[12:13]
	v_add_f32_e32 v8, v8, v9
	v_add_f32_e32 v8, v8, v11
	v_add_f32_e32 v8, v10, v8
	v_lshlrev_b32_e32 v10, 16, v48
	v_and_b32_e32 v11, 0xffff0000, v48
	s_nop 1
	v_add_f32_dpp v8, v8, v8 quad_perm:[1,0,3,2] row_mask:0xf bank_mask:0xf
	s_nop 1
	v_add_f32_dpp v8, v8, v8 quad_perm:[2,3,0,1] row_mask:0xf bank_mask:0xf
	s_nop 1
	v_add_f32_dpp v8, v8, v8 row_half_mirror row_mask:0xf bank_mask:0xf
	v_fmamk_f32 v8, v8, 0x3c800000, v180
	v_mul_f32_e32 v9, 0x4b800000, v8
	v_cmp_gt_f32_e32 vcc, s1, v8
	s_nop 1
	v_cndmask_b32_e32 v8, v8, v9, vcc
	v_rsq_f32_e32 v8, v8
	s_nop 0
	v_mul_f32_e32 v9, 0x45800000, v8
	v_cndmask_b32_e32 v8, v8, v9, vcc
	v_pk_mul_f32 v[0:1], v[0:1], v[8:9] op_sel_hi:[1,0]
	v_pk_mul_f32 v[2:3], v[2:3], v[8:9] op_sel_hi:[1,0]
	v_pk_mul_f32 v[0:1], v[0:1], v[10:11]
	v_lshlrev_b32_e32 v10, 16, v49
	v_and_b32_e32 v11, 0xffff0000, v49
	v_pk_mul_f32 v[2:3], v[2:3], v[10:11]
	v_cvt_pk_bf16_f32 v0, v0, v1
	v_cvt_pk_bf16_f32 v1, v2, v3
	v_pk_mul_f32 v[2:3], v[4:5], v[8:9] op_sel_hi:[1,0]
	v_lshlrev_b32_e32 v4, 16, v50
	v_and_b32_e32 v5, 0xffff0000, v50
	v_pk_mul_f32 v[2:3], v[2:3], v[4:5]
	v_pk_mul_f32 v[4:5], v[6:7], v[8:9] op_sel_hi:[1,0]
	v_lshlrev_b32_e32 v6, 16, v51
	v_and_b32_e32 v7, 0xffff0000, v51
	v_pk_mul_f32 v[4:5], v[4:5], v[6:7]
	v_cvt_pk_bf16_f32 v2, v2, v3
	v_cvt_pk_bf16_f32 v3, v4, v5
	v_lshl_add_u64 v[4:5], s[26:27], 0, v[38:39]
	v_lshl_add_u64 v[4:5], v[4:5], 0, s[60:61]
	v_lshl_add_u64 v[4:5], v[4:5], 0, v[80:81]
	global_store_dwordx4 v[4:5], v[0:3], off sc1
	s_nop 1
	ds_read_b128 v[0:3], v16 offset:6528
	ds_read_b128 v[4:7], v16 offset:6544
	s_waitcnt lgkmcnt(1)
	v_pk_mul_f32 v[8:9], v[2:3], v[2:3]
	v_pk_mul_f32 v[10:11], v[0:1], v[0:1]
	s_nop 0
	v_pk_mov_b32 v[12:13], v[10:11], v[8:9] op_sel:[1,0]
	v_mov_b32_e32 v11, v9
	v_pk_add_f32 v[8:9], v[12:13], v[10:11]
	s_waitcnt lgkmcnt(0)
	v_pk_mul_f32 v[10:11], v[6:7], v[6:7]
	v_pk_mul_f32 v[12:13], v[4:5], v[4:5]
	v_mov_b32_e32 v14, v10
	v_mov_b32_e32 v15, v12
	v_mov_b32_e32 v12, v11
	v_pk_add_f32 v[10:11], v[14:15], v[12:13]
	v_add_f32_e32 v8, v8, v9
	v_add_f32_e32 v8, v8, v11
	v_add_f32_e32 v8, v10, v8
	v_lshlrev_b32_e32 v10, 16, v32
	v_and_b32_e32 v11, 0xffff0000, v32
	s_nop 1
	v_add_f32_dpp v8, v8, v8 quad_perm:[1,0,3,2] row_mask:0xf bank_mask:0xf
	s_nop 1
	v_add_f32_dpp v8, v8, v8 quad_perm:[2,3,0,1] row_mask:0xf bank_mask:0xf
	s_nop 1
	v_add_f32_dpp v8, v8, v8 row_half_mirror row_mask:0xf bank_mask:0xf
	v_fmamk_f32 v8, v8, 0x3c800000, v180
	v_mul_f32_e32 v9, 0x4b800000, v8
	v_cmp_gt_f32_e32 vcc, s1, v8
	s_nop 1
	v_cndmask_b32_e32 v8, v8, v9, vcc
	v_rsq_f32_e32 v8, v8
	s_nop 0
	v_mul_f32_e32 v9, 0x45800000, v8
	v_cndmask_b32_e32 v8, v8, v9, vcc
	v_pk_mul_f32 v[0:1], v[0:1], v[8:9] op_sel_hi:[1,0]
	v_pk_mul_f32 v[2:3], v[2:3], v[8:9] op_sel_hi:[1,0]
	v_pk_mul_f32 v[0:1], v[0:1], v[10:11]
	v_lshlrev_b32_e32 v10, 16, v33
	v_and_b32_e32 v11, 0xffff0000, v33
	v_pk_mul_f32 v[2:3], v[2:3], v[10:11]
	v_cvt_pk_bf16_f32 v0, v0, v1
	v_cvt_pk_bf16_f32 v1, v2, v3
	v_pk_mul_f32 v[2:3], v[4:5], v[8:9] op_sel_hi:[1,0]
	v_lshlrev_b32_e32 v4, 16, v34
	v_and_b32_e32 v5, 0xffff0000, v34
	v_pk_mul_f32 v[2:3], v[2:3], v[4:5]
	v_pk_mul_f32 v[4:5], v[6:7], v[8:9] op_sel_hi:[1,0]
	v_lshlrev_b32_e32 v6, 16, v35
	v_and_b32_e32 v7, 0xffff0000, v35
	v_pk_mul_f32 v[4:5], v[4:5], v[6:7]
	v_cvt_pk_bf16_f32 v2, v2, v3
	v_cvt_pk_bf16_f32 v3, v4, v5
	v_lshl_add_u64 v[4:5], s[26:27], 0, v[36:37]
	v_lshl_add_u64 v[4:5], v[4:5], 0, s[60:61]
	v_lshl_add_u64 v[4:5], v[4:5], 0, v[80:81]
	global_store_dwordx4 v[4:5], v[0:3], off sc1
	s_nop 1
	s_waitcnt vmcnt(0)
	s_barrier

.LBB0_294:
	s_mul_i32 s55, s33, 0x5000
	s_add_i32 s0, s55, 0
	v_add_u32_e32 v68, s0, v122
	s_barrier
	v_add_u32_e32 v48, v68, v125
	v_add_u32_e32 v69, v68, v126
	v_add_u32_e32 v70, v68, v127
	v_add_u32_e32 v68, v68, v128
	v_add_u32_e32 v130, s0, v129
	ds_read_b128 v[192:195], v48
	ds_read_b128 v[196:199], v69
	ds_read_b128 v[200:203], v70
	ds_read_b128 v[208:211], v68
	ds_read_b128 v[98:101], v48 offset:4096
	ds_read_b128 v[102:105], v69 offset:4096
	ds_read_b128 v[106:109], v70 offset:4096
	ds_read_b128 v[132:135], v68 offset:4096
	s_waitcnt lgkmcnt(7)
	v_mfma_f32_32x32x16_bf16 v[48:63], v[192:195], v[82:85], v[32:47]
	s_waitcnt lgkmcnt(6)
	v_mfma_f32_32x32x16_bf16 v[48:63], v[196:199], v[86:89], v[48:63]
	s_waitcnt lgkmcnt(5)
	v_mfma_f32_32x32x16_bf16 v[48:63], v[200:203], v[90:93], v[48:63]
	s_waitcnt lgkmcnt(4)
	v_mfma_f32_32x32x16_bf16 v[48:63], v[208:211], v[94:97], v[48:63]
	s_waitcnt lgkmcnt(3)
	v_mfma_f32_32x32x16_bf16 v[64:79], v[98:101], v[82:85], v[32:47]
	s_waitcnt lgkmcnt(2)
	v_mfma_f32_32x32x16_bf16 v[64:79], v[102:105], v[86:89], v[64:79]
	ds_read_b64_tr_b16 v[110:111], v130 offset:12288
	ds_read_b64_tr_b16 v[112:113], v130 offset:12800
	ds_read_b64_tr_b16 v[102:103], v130 offset:13312
	ds_read_b64_tr_b16 v[104:105], v130 offset:13824
	s_waitcnt lgkmcnt(5)
	v_mfma_f32_32x32x16_bf16 v[64:79], v[106:109], v[90:93], v[64:79]
	s_nop 1
	v_max_f32_e32 v98, v49, v49
	v_max_f32_e32 v99, v48, v48
	v_max_f32_e32 v98, v99, v98
	v_max3_f32 v98, v98, v50, v51
	v_max3_f32 v98, v98, v52, v53
	v_max3_f32 v98, v98, v54, v55
	v_max3_f32 v98, v98, v56, v57
	s_waitcnt lgkmcnt(4)
	v_mfma_f32_32x32x16_bf16 v[64:79], v[132:135], v[94:97], v[64:79]
	v_max3_f32 v98, v98, v58, v59
	v_max3_f32 v98, v98, v60, v61
	v_max3_f32 v98, v98, v62, v63
	s_nop 8
	v_max3_f32 v98, v98, v64, v65
	v_max3_f32 v98, v98, v66, v67
	v_max3_f32 v98, v98, v68, v69
	v_max3_f32 v98, v98, v70, v71
	v_max3_f32 v98, v98, v72, v73
	v_max3_f32 v98, v98, v74, v75
	v_max3_f32 v98, v98, v76, v77
	v_max3_f32 v131, v98, v78, v79
	ds_read_b64_tr_b16 v[106:107], v130 offset:14336
	ds_read_b64_tr_b16 v[108:109], v130 offset:14848
	ds_read_b64_tr_b16 v[98:99], v130 offset:15360
	ds_read_b64_tr_b16 v[100:101], v130 offset:15872
	s_waitcnt lgkmcnt(4)
	ds_read_b64_tr_b16 v[212:213], v130 offset:16384
	ds_read_b64_tr_b16 v[214:215], v130 offset:16896
	ds_read_b64_tr_b16 v[224:225], v130 offset:17408
	ds_read_b64_tr_b16 v[226:227], v130 offset:17920
	ds_read_b64_tr_b16 v[228:229], v130 offset:18432
	ds_read_b64_tr_b16 v[230:231], v130 offset:18944
	ds_read_b64_tr_b16 v[232:233], v130 offset:19456
	ds_read_b64_tr_b16 v[234:235], v130 offset:19968
	v_cmp_lt_f32_e32 vcc, s72, v131
	s_cbranch_vccz .LBB0_298
	ds_bpermute_b32 v132, v219, v131
	s_waitcnt lgkmcnt(0)
	v_max_f32_e32 v132, v132, v132
	v_max_f32_e32 v131, v131, v132
	v_max_f32_e32 v32, v131, v131
	v_max_f32_e32 v32, 0, v32
	v_exp_f32_e64 v33, -v32
	s_and_saveexec_b64 s[44:45], s[40:41]
	ds_write_b32 v123, v33
	s_or_b64 exec, exec, s[44:45]
	s_waitcnt lgkmcnt(0)
	ds_read_b128 v[34:37], v124
	ds_read_b128 v[38:41], v124 offset:32
	ds_read_b128 v[42:45], v124 offset:64
	ds_read_b128 v[132:135], v124 offset:96
	v_pk_add_f32 v[48:49], v[48:49], v[32:33] op_sel_hi:[1,0] neg_lo:[0,1] neg_hi:[0,1]
	v_pk_add_f32 v[64:65], v[64:65], v[32:33] op_sel_hi:[1,0] neg_lo:[0,1] neg_hi:[0,1]
	v_pk_add_f32 v[50:51], v[50:51], v[32:33] op_sel_hi:[1,0] neg_lo:[0,1] neg_hi:[0,1]
	v_pk_add_f32 v[66:67], v[66:67], v[32:33] op_sel_hi:[1,0] neg_lo:[0,1] neg_hi:[0,1]
	v_pk_add_f32 v[52:53], v[52:53], v[32:33] op_sel_hi:[1,0] neg_lo:[0,1] neg_hi:[0,1]
	v_pk_add_f32 v[68:69], v[68:69], v[32:33] op_sel_hi:[1,0] neg_lo:[0,1] neg_hi:[0,1]
	v_pk_add_f32 v[54:55], v[54:55], v[32:33] op_sel_hi:[1,0] neg_lo:[0,1] neg_hi:[0,1]
	v_pk_add_f32 v[70:71], v[70:71], v[32:33] op_sel_hi:[1,0] neg_lo:[0,1] neg_hi:[0,1]
	v_pk_add_f32 v[56:57], v[56:57], v[32:33] op_sel_hi:[1,0] neg_lo:[0,1] neg_hi:[0,1]
	v_pk_add_f32 v[72:73], v[72:73], v[32:33] op_sel_hi:[1,0] neg_lo:[0,1] neg_hi:[0,1]
	v_pk_add_f32 v[58:59], v[58:59], v[32:33] op_sel_hi:[1,0] neg_lo:[0,1] neg_hi:[0,1]
	v_pk_add_f32 v[74:75], v[74:75], v[32:33] op_sel_hi:[1,0] neg_lo:[0,1] neg_hi:[0,1]
	v_pk_add_f32 v[60:61], v[60:61], v[32:33] op_sel_hi:[1,0] neg_lo:[0,1] neg_hi:[0,1]
	v_pk_add_f32 v[76:77], v[76:77], v[32:33] op_sel_hi:[1,0] neg_lo:[0,1] neg_hi:[0,1]
	v_pk_add_f32 v[62:63], v[62:63], v[32:33] op_sel_hi:[1,0] neg_lo:[0,1] neg_hi:[0,1]
	v_pk_add_f32 v[78:79], v[78:79], v[32:33] op_sel_hi:[1,0] neg_lo:[0,1] neg_hi:[0,1]
	v_pk_add_f32 v[136:137], v[114:115], v[32:33]
	v_pk_mul_f32 v[32:33], v[114:115], v[32:33]
	s_waitcnt lgkmcnt(3)
	v_pk_mul_f32 v[0:1], v[0:1], v[34:35]
	v_mov_b32_e32 v137, v33
	v_pk_add_f32 v[46:47], v[136:137], 0 neg_lo:[1,1] neg_hi:[1,1]
	v_pk_mul_f32 v[2:3], v[2:3], v[36:37]
	s_waitcnt lgkmcnt(2)
	v_pk_mul_f32 v[4:5], v[4:5], v[38:39]
	v_pk_mul_f32 v[6:7], v[6:7], v[40:41]
	s_waitcnt lgkmcnt(1)
	v_pk_mul_f32 v[8:9], v[8:9], v[42:43]
	v_pk_mul_f32 v[10:11], v[10:11], v[44:45]
	s_waitcnt lgkmcnt(0)
	v_pk_mul_f32 v[12:13], v[12:13], v[132:133]
	v_pk_mul_f32 v[14:15], v[14:15], v[134:135]
	v_pk_mul_f32 v[30:31], v[30:31], v[134:135]
	v_pk_mul_f32 v[26:27], v[26:27], v[44:45]
	v_pk_mul_f32 v[22:23], v[22:23], v[40:41]
	v_pk_mul_f32 v[18:19], v[18:19], v[36:37]
	v_pk_mul_f32 v[28:29], v[28:29], v[132:133]
	v_pk_mul_f32 v[24:25], v[24:25], v[42:43]
	v_pk_mul_f32 v[20:21], v[20:21], v[38:39]
	v_pk_mul_f32 v[16:17], v[16:17], v[34:35]
	v_mov_b32_e32 v47, v46
	v_mov_b32_e32 v45, v46
	v_mov_b32_e32 v44, v46
	v_mov_b32_e32 v43, v46
	v_mov_b32_e32 v42, v46
	v_mov_b32_e32 v41, v46
	v_mov_b32_e32 v40, v46
	v_mov_b32_e32 v39, v46
	v_mov_b32_e32 v38, v46
	v_mov_b32_e32 v37, v46
	v_mov_b32_e32 v36, v46
	v_mov_b32_e32 v35, v46
	v_mov_b32_e32 v34, v46
	v_mov_b32_e32 v33, v46
	v_mov_b32_e32 v32, v46
	v_mov_b64_e32 v[114:115], v[136:137]

.LBB0_345:
	s_mul_i32 s54, s11, 0x5000
	s_add_i32 s0, s54, 0
	v_add_u32_e32 v68, s0, v132
	s_barrier
	v_add_u32_e32 v69, v68, v136
	v_add_u32_e32 v110, v68, v137
	v_add_u32_e32 v111, v68, v138
	v_add_u32_e32 v112, v68, v139
	v_add_u32_e32 v68, s0, v133
	v_add_u32_e32 v113, v68, v140
	v_add_u32_e32 v118, v68, v141
	v_add_u32_e32 v143, s0, v142
	ds_read_b128 v[190:193], v69
	ds_read_b128 v[194:197], v110
	ds_read_b128 v[198:201], v111
	ds_read_b128 v[208:211], v112
	ds_read_b128 v[212:215], v113 offset:8192
	ds_read_b128 v[222:225], v118 offset:8192
	ds_read_b128 v[226:229], v69 offset:4096
	ds_read_b128 v[230:233], v110 offset:4096
	ds_read_b128 v[234:237], v111 offset:4096
	ds_read_b128 v[238:241], v112 offset:4096
	ds_read_b128 v[242:245], v113 offset:10240
	ds_read_b128 v[246:249], v118 offset:10240
	s_waitcnt lgkmcnt(11)
	v_mfma_f32_32x32x16_bf16 v[48:63], v[190:193], v[82:85], v[16:31]
	s_waitcnt lgkmcnt(10)
	v_mfma_f32_32x32x16_bf16 v[48:63], v[194:197], v[86:89], v[48:63]
	s_waitcnt lgkmcnt(9)
	v_mfma_f32_32x32x16_bf16 v[48:63], v[198:201], v[90:93], v[48:63]
	s_waitcnt lgkmcnt(8)
	v_mfma_f32_32x32x16_bf16 v[48:63], v[208:211], v[94:97], v[48:63]
	s_waitcnt lgkmcnt(7)
	v_mfma_f32_32x32x16_bf16 v[48:63], v[212:215], v[98:101], v[48:63]
	s_waitcnt lgkmcnt(6)
	v_mfma_f32_32x32x16_bf16 v[48:63], v[222:225], v[102:105], v[48:63]
	s_waitcnt lgkmcnt(5)
	v_mfma_f32_32x32x16_bf16 v[64:79], v[226:229], v[82:85], v[16:31]
	s_waitcnt lgkmcnt(4)
	v_mfma_f32_32x32x16_bf16 v[64:79], v[230:233], v[86:89], v[64:79]
	ds_read_b64_tr_b16 v[118:119], v143 offset:12288
	ds_read_b64_tr_b16 v[120:121], v143 offset:12800
	ds_read_b64_tr_b16 v[110:111], v143 offset:13312
	ds_read_b64_tr_b16 v[112:113], v143 offset:13824
	s_waitcnt lgkmcnt(7)
	v_mfma_f32_32x32x16_bf16 v[64:79], v[234:237], v[90:93], v[64:79]
	s_waitcnt lgkmcnt(6)
	v_mfma_f32_32x32x16_bf16 v[64:79], v[238:241], v[94:97], v[64:79]
	v_max_f32_e32 v106, v49, v49
	v_max_f32_e32 v107, v48, v48
	v_max_f32_e32 v106, v107, v106
	v_max3_f32 v106, v106, v50, v51
	v_max3_f32 v106, v106, v52, v53
	v_max3_f32 v106, v106, v54, v55
	v_max3_f32 v106, v106, v56, v57
	s_waitcnt lgkmcnt(5)
	v_mfma_f32_32x32x16_bf16 v[64:79], v[242:245], v[98:101], v[64:79]
	v_max3_f32 v106, v106, v58, v59
	v_max3_f32 v106, v106, v60, v61
	v_max3_f32 v106, v106, v62, v63
	s_waitcnt lgkmcnt(4)
	v_mfma_f32_32x32x16_bf16 v[64:79], v[246:249], v[102:105], v[64:79]
	s_nop 11
	v_max3_f32 v106, v106, v64, v65
	v_max3_f32 v106, v106, v66, v67
	v_max3_f32 v106, v106, v68, v69
	v_max3_f32 v106, v106, v70, v71
	v_max3_f32 v106, v106, v72, v73
	v_max3_f32 v106, v106, v74, v75
	v_max3_f32 v106, v106, v76, v77
	v_max3_f32 v144, v106, v78, v79
	ds_read_b64_tr_b16 v[114:115], v143 offset:14336
	ds_read_b64_tr_b16 v[116:117], v143 offset:14848
	ds_read_b64_tr_b16 v[106:107], v143 offset:15360
	ds_read_b64_tr_b16 v[108:109], v143 offset:15872
	s_waitcnt lgkmcnt(4)
	ds_read_b64_tr_b16 v[190:191], v143 offset:16384
	ds_read_b64_tr_b16 v[192:193], v143 offset:16896
	ds_read_b64_tr_b16 v[194:195], v143 offset:17408
	ds_read_b64_tr_b16 v[196:197], v143 offset:17920
	ds_read_b64_tr_b16 v[198:199], v143 offset:18432
	ds_read_b64_tr_b16 v[200:201], v143 offset:18944
	ds_read_b64_tr_b16 v[208:209], v143 offset:19456
	ds_read_b64_tr_b16 v[210:211], v143 offset:19968
	v_cmp_lt_f32_e32 vcc, s72, v144
	s_cbranch_vccz .LBB0_349
	ds_bpermute_b32 v145, v219, v144
	s_waitcnt lgkmcnt(0)
	v_max_f32_e32 v145, v145, v145
	v_max_f32_e32 v144, v144, v145
	v_max_f32_e32 v16, v144, v144
	v_max_f32_e32 v16, 0, v16
	v_exp_f32_e64 v17, -v16
	s_and_saveexec_b64 s[28:29], s[40:41]
	ds_write_b32 v134, v17
	s_or_b64 exec, exec, s[28:29]
	s_waitcnt lgkmcnt(0)
	ds_read_b128 v[18:21], v135
	ds_read_b128 v[22:25], v135 offset:32
	ds_read_b128 v[26:29], v135 offset:64
	ds_read_b128 v[144:147], v135 offset:96
	v_pk_add_f32 v[48:49], v[48:49], v[16:17] op_sel_hi:[1,0] neg_lo:[0,1] neg_hi:[0,1]
	v_pk_add_f32 v[64:65], v[64:65], v[16:17] op_sel_hi:[1,0] neg_lo:[0,1] neg_hi:[0,1]
	v_pk_add_f32 v[50:51], v[50:51], v[16:17] op_sel_hi:[1,0] neg_lo:[0,1] neg_hi:[0,1]
	v_pk_add_f32 v[66:67], v[66:67], v[16:17] op_sel_hi:[1,0] neg_lo:[0,1] neg_hi:[0,1]
	v_pk_add_f32 v[52:53], v[52:53], v[16:17] op_sel_hi:[1,0] neg_lo:[0,1] neg_hi:[0,1]
	v_pk_add_f32 v[68:69], v[68:69], v[16:17] op_sel_hi:[1,0] neg_lo:[0,1] neg_hi:[0,1]
	v_pk_add_f32 v[54:55], v[54:55], v[16:17] op_sel_hi:[1,0] neg_lo:[0,1] neg_hi:[0,1]
	v_pk_add_f32 v[70:71], v[70:71], v[16:17] op_sel_hi:[1,0] neg_lo:[0,1] neg_hi:[0,1]
	v_pk_add_f32 v[56:57], v[56:57], v[16:17] op_sel_hi:[1,0] neg_lo:[0,1] neg_hi:[0,1]
	v_pk_add_f32 v[72:73], v[72:73], v[16:17] op_sel_hi:[1,0] neg_lo:[0,1] neg_hi:[0,1]
	v_pk_add_f32 v[58:59], v[58:59], v[16:17] op_sel_hi:[1,0] neg_lo:[0,1] neg_hi:[0,1]
	v_pk_add_f32 v[74:75], v[74:75], v[16:17] op_sel_hi:[1,0] neg_lo:[0,1] neg_hi:[0,1]
	v_pk_add_f32 v[60:61], v[60:61], v[16:17] op_sel_hi:[1,0] neg_lo:[0,1] neg_hi:[0,1]
	v_pk_add_f32 v[76:77], v[76:77], v[16:17] op_sel_hi:[1,0] neg_lo:[0,1] neg_hi:[0,1]
	v_pk_add_f32 v[62:63], v[62:63], v[16:17] op_sel_hi:[1,0] neg_lo:[0,1] neg_hi:[0,1]
	v_pk_add_f32 v[78:79], v[78:79], v[16:17] op_sel_hi:[1,0] neg_lo:[0,1] neg_hi:[0,1]
	v_pk_add_f32 v[152:153], v[122:123], v[16:17]
	v_pk_mul_f32 v[16:17], v[122:123], v[16:17]
	s_waitcnt lgkmcnt(3)
	v_pk_mul_f32 v[0:1], v[0:1], v[18:19]
	v_mov_b32_e32 v153, v17
	v_pk_add_f32 v[30:31], v[152:153], 0 neg_lo:[1,1] neg_hi:[1,1]
	v_pk_mul_f32 v[2:3], v[2:3], v[20:21]
	s_waitcnt lgkmcnt(2)
	v_pk_mul_f32 v[4:5], v[4:5], v[22:23]
	v_pk_mul_f32 v[6:7], v[6:7], v[24:25]
	s_waitcnt lgkmcnt(1)
	v_pk_mul_f32 v[8:9], v[8:9], v[26:27]
	v_pk_mul_f32 v[10:11], v[10:11], v[28:29]
	s_waitcnt lgkmcnt(0)
	v_pk_mul_f32 v[12:13], v[12:13], v[144:145]
	v_pk_mul_f32 v[14:15], v[14:15], v[146:147]
	v_pk_mul_f32 v[46:47], v[46:47], v[146:147]
	v_pk_mul_f32 v[42:43], v[42:43], v[28:29]
	v_pk_mul_f32 v[38:39], v[38:39], v[24:25]
	v_pk_mul_f32 v[34:35], v[34:35], v[20:21]
	v_pk_mul_f32 v[44:45], v[44:45], v[144:145]
	v_pk_mul_f32 v[40:41], v[40:41], v[26:27]
	v_pk_mul_f32 v[36:37], v[36:37], v[22:23]
	v_pk_mul_f32 v[32:33], v[32:33], v[18:19]
	v_mov_b32_e32 v31, v30
	v_mov_b32_e32 v29, v30
	v_mov_b32_e32 v28, v30
	v_mov_b32_e32 v27, v30
	v_mov_b32_e32 v26, v30
	v_mov_b32_e32 v25, v30
	v_mov_b32_e32 v24, v30
	v_mov_b32_e32 v23, v30
	v_mov_b32_e32 v22, v30
	v_mov_b32_e32 v21, v30
	v_mov_b32_e32 v20, v30
	v_mov_b32_e32 v19, v30
	v_mov_b32_e32 v18, v30
	v_mov_b32_e32 v17, v30
	v_mov_b32_e32 v16, v30
	v_mov_b64_e32 v[122:123], v[152:153]

.LBB0_561:
	v_lshrrev_b32_e32 v22, 4, v26
	v_lshrrev_b32_e32 v23, 1, v26
	v_bitop3_b32 v27, v23, v22, 7 bitop3:0x6c
	v_add_u32_e32 v22, 4, v22
	v_bitop3_b32 v22, v22, v23, 7 bitop3:0x78
	v_lshlrev_b32_e32 v224, 4, v22
	v_and_b32_e32 v22, 15, v26
	v_readlane_b32 s0, v255, 19
	s_add_u32 s34, s65, 0x2c00080
	s_addc_u32 s35, 0, 0
	v_or_b32_e32 v23, s0, v22
	v_or_b32_e32 v22, s95, v22
	v_lshlrev_b32_e32 v226, 7, v22
	v_lshlrev_b32_e32 v22, 10, v24
	v_readlane_b32 s0, v255, 29
	v_add3_u32 v22, s44, v22, v25
	s_add_u32 s28, s0, s28
	v_readlane_b32 s0, v255, 30
	v_lshlrev_b32_e32 v227, 7, v23
	s_cbranch_vccnz .Lg1_skipw1
	s_waitcnt vmcnt(0)
.Lg1_skipw1:
	v_ashrrev_i32_e32 v23, 31, v22
	v_lshlrev_b64 v[16:17], 1, v[16:17]
	s_addc_u32 s29, s0, s29
	v_lshlrev_b64 v[18:19], 1, v[18:19]
	v_lshlrev_b64 v[20:21], 1, v[20:21]
	v_lshlrev_b64 v[22:23], 1, v[22:23]
	v_lshl_add_u64 v[194:195], s[34:35], 0, v[16:17]
	v_lshl_add_u64 v[202:203], s[28:29], 0, v[16:17]
	v_mov_b32_e32 v16, 0
	v_lshlrev_b32_e32 v225, 4, v27
	v_lshl_add_u64 v[150:151], s[34:35], 0, v[18:19]
	v_lshl_add_u64 v[190:191], s[34:35], 0, v[20:21]
	v_lshl_add_u64 v[192:193], s[34:35], 0, v[22:23]
	v_lshl_add_u64 v[196:197], s[28:29], 0, v[18:19]
	v_lshl_add_u64 v[198:199], s[28:29], 0, v[20:21]
	v_lshl_add_u64 v[200:201], s[28:29], 0, v[22:23]
	s_mov_b32 s9, 0
	v_mov_b32_e32 v17, v16
	v_mov_b32_e32 v18, v16
	v_mov_b32_e32 v19, v16
	v_mov_b32_e32 v20, v16
	v_mov_b32_e32 v21, v16
	v_mov_b32_e32 v22, v16
	v_mov_b32_e32 v23, v16
	v_mov_b32_e32 v24, v16
	v_mov_b32_e32 v25, v16
	v_mov_b32_e32 v26, v16
	v_mov_b32_e32 v27, v16
	v_mov_b32_e32 v28, v16
	v_mov_b32_e32 v29, v16
	v_mov_b32_e32 v30, v16
	v_mov_b32_e32 v31, v16
	v_mov_b32_e32 v86, v16
	v_mov_b32_e32 v87, v16
	v_mov_b32_e32 v88, v16
	v_mov_b32_e32 v89, v16
	v_mov_b32_e32 v90, v16
	v_mov_b32_e32 v91, v16
	v_mov_b32_e32 v92, v16
	v_mov_b32_e32 v93, v16
	v_mov_b32_e32 v94, v16
	v_mov_b32_e32 v95, v16
	v_mov_b32_e32 v96, v16
	v_mov_b32_e32 v97, v16
	v_mov_b32_e32 v98, v16
	v_mov_b32_e32 v99, v16
	v_mov_b32_e32 v100, v16
	v_mov_b32_e32 v101, v16
	v_mov_b32_e32 v32, v16
	v_mov_b32_e32 v33, v16
	v_mov_b32_e32 v34, v16
	v_mov_b32_e32 v35, v16
	v_mov_b32_e32 v36, v16
	v_mov_b32_e32 v37, v16
	v_mov_b32_e32 v38, v16
	v_mov_b32_e32 v39, v16
	v_mov_b32_e32 v40, v16
	v_mov_b32_e32 v41, v16
	v_mov_b32_e32 v42, v16
	v_mov_b32_e32 v43, v16
	v_mov_b32_e32 v44, v16
	v_mov_b32_e32 v45, v16
	v_mov_b32_e32 v46, v16
	v_mov_b32_e32 v47, v16
	v_mov_b32_e32 v102, v16
	v_mov_b32_e32 v103, v16
	v_mov_b32_e32 v104, v16
	v_mov_b32_e32 v105, v16
	v_mov_b32_e32 v106, v16
	v_mov_b32_e32 v107, v16
	v_mov_b32_e32 v108, v16
	v_mov_b32_e32 v109, v16
	v_mov_b32_e32 v110, v16
	v_mov_b32_e32 v111, v16
	v_mov_b32_e32 v112, v16
	v_mov_b32_e32 v113, v16
	v_mov_b32_e32 v114, v16
	v_mov_b32_e32 v115, v16
	v_mov_b32_e32 v116, v16
	v_mov_b32_e32 v117, v16
	v_mov_b32_e32 v48, v16
	v_mov_b32_e32 v49, v16
	v_mov_b32_e32 v50, v16
	v_mov_b32_e32 v51, v16
	v_mov_b32_e32 v52, v16
	v_mov_b32_e32 v53, v16
	v_mov_b32_e32 v54, v16
	v_mov_b32_e32 v55, v16
	v_mov_b32_e32 v56, v16
	v_mov_b32_e32 v57, v16
	v_mov_b32_e32 v58, v16
	v_mov_b32_e32 v59, v16
	v_mov_b32_e32 v60, v16
	v_mov_b32_e32 v61, v16
	v_mov_b32_e32 v62, v16
	v_mov_b32_e32 v63, v16
	v_mov_b32_e32 v118, v16
	v_mov_b32_e32 v119, v16
	v_mov_b32_e32 v120, v16
	v_mov_b32_e32 v121, v16
	v_mov_b32_e32 v122, v16
	v_mov_b32_e32 v123, v16
	v_mov_b32_e32 v124, v16
	v_mov_b32_e32 v125, v16
	v_mov_b32_e32 v126, v16
	v_mov_b32_e32 v127, v16
	v_mov_b32_e32 v128, v16
	v_mov_b32_e32 v129, v16
	v_mov_b32_e32 v130, v16
	v_mov_b32_e32 v131, v16
	v_mov_b32_e32 v132, v16
	v_mov_b32_e32 v133, v16
	v_mov_b32_e32 v64, v16
	v_mov_b32_e32 v65, v16
	v_mov_b32_e32 v66, v16
	v_mov_b32_e32 v67, v16
	v_mov_b32_e32 v68, v16
	v_mov_b32_e32 v69, v16
	v_mov_b32_e32 v70, v16
	v_mov_b32_e32 v71, v16
	v_mov_b32_e32 v72, v16
	v_mov_b32_e32 v73, v16
	v_mov_b32_e32 v74, v16
	v_mov_b32_e32 v75, v16
	v_mov_b32_e32 v76, v16
	v_mov_b32_e32 v77, v16
	v_mov_b32_e32 v78, v16
	v_mov_b32_e32 v79, v16
	v_mov_b32_e32 v134, v16
	v_mov_b32_e32 v135, v16
	v_mov_b32_e32 v136, v16
	v_mov_b32_e32 v137, v16
	v_mov_b32_e32 v138, v16
	v_mov_b32_e32 v139, v16
	v_mov_b32_e32 v140, v16
	v_mov_b32_e32 v141, v16
	v_mov_b32_e32 v142, v16
	v_mov_b32_e32 v143, v16
	v_mov_b32_e32 v144, v16
	v_mov_b32_e32 v145, v16
	v_mov_b32_e32 v146, v16
	v_mov_b32_e32 v147, v16
	v_mov_b32_e32 v148, v16
	v_mov_b32_e32 v149, v16
	s_waitcnt lgkmcnt(0)
	s_cbranch_vccnz .Lg1_skipw2
	s_waitcnt vmcnt(0)
.Lg1_skipw2:
	s_barrier
.LBB0_562:
	s_and_b32 s0, s9, 0x10000
	s_add_i32 s17, s0, 0
	v_add_u32_e32 v240, s17, v227
	v_add_u32_e32 v241, s17, v226
	s_xor_b32 s0, s0, 0x10000
	s_add_i32 s0, s96, s0
	v_add_u32_e32 v164, v240, v225
	v_add_u32_e32 v242, v241, v225
	s_add_i32 s17, s0, 0x8000
	ds_read_b128 v[176:179], v164
	ds_read_b128 v[172:175], v164 offset:2048
	ds_read_b128 v[168:171], v164 offset:4096
	ds_read_b128 v[164:167], v164 offset:6144
	ds_read_b128 v[182:185], v242 offset:32768
	ds_read_b128 v[208:211], v242 offset:34816
	ds_read_b128 v[212:215], v242 offset:36864
	ds_read_b128 v[228:231], v242 offset:38912
	v_lshl_add_u64 v[238:239], s[88:89], 0, v[200:201]
	s_mov_b32 m0, s0
	s_add_i32 s29, s0, 0x400
	v_lshl_add_u64 v[236:237], s[88:89], 0, v[192:193]
	global_load_lds_dwordx4 v[238:239], off
	s_mov_b32 m0, s17
	s_add_i32 s28, s0, 0x8400
	v_lshl_add_u64 v[234:235], s[88:89], 0, v[202:203]
	global_load_lds_dwordx4 v[236:237], off
	s_mov_b32 m0, s29
	v_lshl_add_u64 v[232:233], s[88:89], 0, v[194:195]
	global_load_lds_dwordx4 v[234:235], off
	s_mov_b32 m0, s28
	s_add_i32 s29, s0, 0x8800
	global_load_lds_dwordx4 v[232:233], off
	s_add_i32 m0, s0, 0x800
	v_lshl_add_u64 v[238:239], s[88:89], 0, v[196:197]
	s_waitcnt lgkmcnt(0)
	v_mfma_f32_16x16x32_bf16 v[146:149], v[176:179], v[182:185], v[146:149]
	s_add_i32 s28, s0, 0xc00
	v_lshl_add_u64 v[236:237], s[88:89], 0, v[150:151]
	s_add_i32 s17, s0, 0x8c00
	v_mfma_f32_16x16x32_bf16 v[142:145], v[176:179], v[208:211], v[142:145]
	v_lshl_add_u64 v[234:235], s[88:89], 0, v[198:199]
	v_lshl_add_u64 v[232:233], s[88:89], 0, v[190:191]
	s_add_i32 s9, s9, 0x10000
	v_mfma_f32_16x16x32_bf16 v[138:141], v[176:179], v[212:215], v[138:141]
	v_lshl_add_u64 v[150:151], v[150:151], 0, s[22:23]
	v_lshl_add_u64 v[190:191], v[190:191], 0, s[22:23]
	v_lshl_add_u64 v[192:193], v[192:193], 0, s[22:23]
	v_mfma_f32_16x16x32_bf16 v[134:137], v[176:179], v[228:231], v[134:137]
	v_lshl_add_u64 v[194:195], v[194:195], 0, s[22:23]
	v_lshl_add_u64 v[196:197], v[196:197], 0, s[22:23]
	v_lshl_add_u64 v[198:199], v[198:199], 0, s[22:23]
	v_mfma_f32_16x16x32_bf16 v[130:133], v[172:175], v[182:185], v[130:133]
	v_lshl_add_u64 v[200:201], v[200:201], 0, s[22:23]
	v_lshl_add_u64 v[202:203], v[202:203], 0, s[22:23]
	s_cmp_eq_u32 s9, 0xf0000
	v_mfma_f32_16x16x32_bf16 v[126:129], v[172:175], v[208:211], v[126:129]
	v_mfma_f32_16x16x32_bf16 v[122:125], v[172:175], v[212:215], v[122:125]
	v_mfma_f32_16x16x32_bf16 v[118:121], v[172:175], v[228:231], v[118:121]
	v_mfma_f32_16x16x32_bf16 v[114:117], v[168:171], v[182:185], v[114:117]
	v_mfma_f32_16x16x32_bf16 v[110:113], v[168:171], v[208:211], v[110:113]
	v_mfma_f32_16x16x32_bf16 v[106:109], v[168:171], v[212:215], v[106:109]
	v_mfma_f32_16x16x32_bf16 v[102:105], v[168:171], v[228:231], v[102:105]
	v_mfma_f32_16x16x32_bf16 v[98:101], v[164:167], v[182:185], v[98:101]
	v_mfma_f32_16x16x32_bf16 v[94:97], v[164:167], v[208:211], v[94:97]
	v_mfma_f32_16x16x32_bf16 v[90:93], v[164:167], v[212:215], v[90:93]
	v_mfma_f32_16x16x32_bf16 v[86:89], v[164:167], v[228:231], v[86:89]
	ds_read_b128 v[182:185], v242 offset:40960
	ds_read_b128 v[208:211], v242 offset:43008
	ds_read_b128 v[212:215], v242 offset:45056
	ds_read_b128 v[228:231], v242 offset:47104
	global_load_lds_dwordx4 v[238:239], off
	s_mov_b32 m0, s29
	s_waitcnt lgkmcnt(0)
	v_mfma_f32_16x16x32_bf16 v[76:79], v[176:179], v[182:185], v[76:79]
	global_load_lds_dwordx4 v[236:237], off
	s_mov_b32 m0, s28
	v_mfma_f32_16x16x32_bf16 v[72:75], v[176:179], v[208:211], v[72:75]
	global_load_lds_dwordx4 v[234:235], off
	s_mov_b32 m0, s17
	v_mfma_f32_16x16x32_bf16 v[68:71], v[176:179], v[212:215], v[68:71]
	global_load_lds_dwordx4 v[232:233], off
	v_add_u32_e32 v232, v241, v224
	v_mfma_f32_16x16x32_bf16 v[64:67], v[176:179], v[228:231], v[64:67]
	v_add_u32_e32 v176, v240, v224
	v_mfma_f32_16x16x32_bf16 v[60:63], v[172:175], v[182:185], v[60:63]
	v_mfma_f32_16x16x32_bf16 v[56:59], v[172:175], v[208:211], v[56:59]
	v_mfma_f32_16x16x32_bf16 v[52:55], v[172:175], v[212:215], v[52:55]
	v_mfma_f32_16x16x32_bf16 v[48:51], v[172:175], v[228:231], v[48:51]
	v_mfma_f32_16x16x32_bf16 v[44:47], v[168:171], v[182:185], v[44:47]
	v_mfma_f32_16x16x32_bf16 v[40:43], v[168:171], v[208:211], v[40:43]
	v_mfma_f32_16x16x32_bf16 v[36:39], v[168:171], v[212:215], v[36:39]
	v_mfma_f32_16x16x32_bf16 v[32:35], v[168:171], v[228:231], v[32:35]
	v_mfma_f32_16x16x32_bf16 v[28:31], v[164:167], v[182:185], v[28:31]
	v_mfma_f32_16x16x32_bf16 v[24:27], v[164:167], v[208:211], v[24:27]
	v_mfma_f32_16x16x32_bf16 v[20:23], v[164:167], v[212:215], v[20:23]
	v_mfma_f32_16x16x32_bf16 v[16:19], v[164:167], v[228:231], v[16:19]
	ds_read_b128 v[164:167], v176
	ds_read_b128 v[168:171], v176 offset:2048
	ds_read_b128 v[172:175], v176 offset:4096
	ds_read_b128 v[176:179], v176 offset:6144
	ds_read_b128 v[182:185], v232 offset:32768
	ds_read_b128 v[208:211], v232 offset:34816
	ds_read_b128 v[212:215], v232 offset:36864
	ds_read_b128 v[228:231], v232 offset:38912
	s_waitcnt lgkmcnt(0)
	v_mfma_f32_16x16x32_bf16 v[146:149], v[164:167], v[182:185], v[146:149]
	v_mfma_f32_16x16x32_bf16 v[142:145], v[164:167], v[208:211], v[142:145]
	v_mfma_f32_16x16x32_bf16 v[138:141], v[164:167], v[212:215], v[138:141]
	v_mfma_f32_16x16x32_bf16 v[134:137], v[164:167], v[228:231], v[134:137]
	v_mfma_f32_16x16x32_bf16 v[130:133], v[168:171], v[182:185], v[130:133]
	v_mfma_f32_16x16x32_bf16 v[126:129], v[168:171], v[208:211], v[126:129]
	v_mfma_f32_16x16x32_bf16 v[122:125], v[168:171], v[212:215], v[122:125]
	v_mfma_f32_16x16x32_bf16 v[118:121], v[168:171], v[228:231], v[118:121]
	v_mfma_f32_16x16x32_bf16 v[114:117], v[172:175], v[182:185], v[114:117]
	v_mfma_f32_16x16x32_bf16 v[110:113], v[172:175], v[208:211], v[110:113]
	v_mfma_f32_16x16x32_bf16 v[106:109], v[172:175], v[212:215], v[106:109]
	v_mfma_f32_16x16x32_bf16 v[102:105], v[172:175], v[228:231], v[102:105]
	v_mfma_f32_16x16x32_bf16 v[98:101], v[176:179], v[182:185], v[98:101]
	v_mfma_f32_16x16x32_bf16 v[94:97], v[176:179], v[208:211], v[94:97]
	v_mfma_f32_16x16x32_bf16 v[90:93], v[176:179], v[212:215], v[90:93]
	v_mfma_f32_16x16x32_bf16 v[86:89], v[176:179], v[228:231], v[86:89]
	ds_read_b128 v[182:185], v232 offset:40960
	ds_read_b128 v[208:211], v232 offset:43008
	ds_read_b128 v[212:215], v232 offset:45056
	ds_read_b128 v[228:231], v232 offset:47104
	s_waitcnt vmcnt(0)
	s_waitcnt vmcnt(0) lgkmcnt(0)
	v_mfma_f32_16x16x32_bf16 v[76:79], v[164:167], v[182:185], v[76:79]
	s_barrier
	v_mfma_f32_16x16x32_bf16 v[72:75], v[164:167], v[208:211], v[72:75]
	v_mfma_f32_16x16x32_bf16 v[68:71], v[164:167], v[212:215], v[68:71]
	v_mfma_f32_16x16x32_bf16 v[64:67], v[164:167], v[228:231], v[64:67]
	v_mfma_f32_16x16x32_bf16 v[60:63], v[168:171], v[182:185], v[60:63]
	v_mfma_f32_16x16x32_bf16 v[56:59], v[168:171], v[208:211], v[56:59]
	v_mfma_f32_16x16x32_bf16 v[52:55], v[168:171], v[212:215], v[52:55]
	v_mfma_f32_16x16x32_bf16 v[48:51], v[168:171], v[228:231], v[48:51]
	v_mfma_f32_16x16x32_bf16 v[44:47], v[172:175], v[182:185], v[44:47]
	v_mfma_f32_16x16x32_bf16 v[40:43], v[172:175], v[208:211], v[40:43]
	v_mfma_f32_16x16x32_bf16 v[36:39], v[172:175], v[212:215], v[36:39]
	v_mfma_f32_16x16x32_bf16 v[32:35], v[172:175], v[228:231], v[32:35]
	v_mfma_f32_16x16x32_bf16 v[28:31], v[176:179], v[182:185], v[28:31]
	v_mfma_f32_16x16x32_bf16 v[24:27], v[176:179], v[208:211], v[24:27]
	v_mfma_f32_16x16x32_bf16 v[20:23], v[176:179], v[212:215], v[20:23]
	v_mfma_f32_16x16x32_bf16 v[16:19], v[176:179], v[228:231], v[16:19]
	s_cbranch_scc0 .LBB0_562
	v_add_u32_e32 v150, s6, v227
	v_add_u32_e32 v202, s6, v226
	v_add_u32_e32 v151, v150, v225
	v_add_u32_e32 v182, v202, v225
	ds_read_b128 v[164:167], v151
	ds_read_b128 v[168:171], v182 offset:32768
	ds_read_b128 v[172:175], v151 offset:2048
	ds_read_b128 v[176:179], v182 offset:34816
	ds_read_b128 v[190:193], v182 offset:36864
	ds_read_b128 v[194:197], v182 offset:38912
	s_waitcnt lgkmcnt(3)
	v_mfma_f32_16x16x32_bf16 v[226:229], v[172:175], v[168:171], v[130:133]
	v_add_u32_e32 v202, v202, v224
	s_and_b32 s0, s79, 31
	s_cmp_eq_u32 s0, s51
	s_waitcnt lgkmcnt(0)
	v_mfma_f32_16x16x32_bf16 v[230:233], v[172:175], v[194:197], v[118:121]
	s_nop 2
	ds_read_b128 v[118:121], v151 offset:4096
	ds_read_b128 v[130:133], v151 offset:6144
	s_cselect_b64 s[28:29], -1, 0
	s_and_b64 s[18:19], s[18:19], s[28:29]
	v_mfma_f32_16x16x32_bf16 v[146:149], v[164:167], v[168:171], v[146:149]
	s_and_b64 vcc, exec, s[18:19]
	v_mfma_f32_16x16x32_bf16 v[142:145], v[164:167], v[176:179], v[142:145]
	v_mfma_f32_16x16x32_bf16 v[138:141], v[164:167], v[190:193], v[138:141]
	v_mfma_f32_16x16x32_bf16 v[126:129], v[172:175], v[176:179], v[126:129]
	v_mfma_f32_16x16x32_bf16 v[122:125], v[172:175], v[190:193], v[122:125]
	s_waitcnt lgkmcnt(1)
	v_mfma_f32_16x16x32_bf16 v[234:237], v[118:121], v[168:171], v[114:117]
	v_mfma_f32_16x16x32_bf16 v[238:241], v[118:121], v[176:179], v[110:113]
	v_mfma_f32_16x16x32_bf16 v[106:109], v[118:121], v[190:193], v[106:109]
	v_mfma_f32_16x16x32_bf16 v[242:245], v[118:121], v[194:197], v[102:105]
	s_waitcnt lgkmcnt(0)
	v_mfma_f32_16x16x32_bf16 v[168:171], v[130:133], v[168:171], v[98:101]
	v_mfma_f32_16x16x32_bf16 v[176:179], v[130:133], v[176:179], v[94:97]
	v_mfma_f32_16x16x32_bf16 v[190:193], v[130:133], v[190:193], v[90:93]
	s_nop 2
	ds_read_b128 v[90:93], v182 offset:40960
	ds_read_b128 v[94:97], v182 offset:43008
	ds_read_b128 v[98:101], v182 offset:45056
	ds_read_b128 v[102:105], v182 offset:47104
	v_mfma_f32_16x16x32_bf16 v[198:201], v[164:167], v[194:197], v[134:137]
	s_waitcnt lgkmcnt(3)
	v_mfma_f32_16x16x32_bf16 v[76:79], v[164:167], v[90:93], v[76:79]
	s_waitcnt lgkmcnt(2)
	v_mfma_f32_16x16x32_bf16 v[72:75], v[164:167], v[94:97], v[72:75]
	s_waitcnt lgkmcnt(1)
	v_mfma_f32_16x16x32_bf16 v[68:71], v[164:167], v[98:101], v[68:71]
	s_waitcnt lgkmcnt(0)
	v_mfma_f32_16x16x32_bf16 v[64:67], v[164:167], v[102:105], v[64:67]
	v_mfma_f32_16x16x32_bf16 v[164:167], v[172:175], v[90:93], v[60:63]
	s_nop 2
	v_add_u32_e32 v60, v150, v224
	v_mfma_f32_16x16x32_bf16 v[182:185], v[130:133], v[94:97], v[24:27]
	s_nop 2
	ds_read_b128 v[24:27], v60
	v_mfma_f32_16x16x32_bf16 v[86:89], v[130:133], v[194:197], v[86:89]
	v_mfma_f32_16x16x32_bf16 v[56:59], v[172:175], v[94:97], v[56:59]
	v_mfma_f32_16x16x32_bf16 v[52:55], v[172:175], v[98:101], v[52:55]
	v_mfma_f32_16x16x32_bf16 v[48:51], v[172:175], v[102:105], v[48:51]
	v_mfma_f32_16x16x32_bf16 v[172:175], v[118:121], v[90:93], v[44:47]
	v_mfma_f32_16x16x32_bf16 v[194:197], v[118:121], v[94:97], v[40:43]
	v_mfma_f32_16x16x32_bf16 v[246:249], v[130:133], v[90:93], v[28:31]
	v_mfma_f32_16x16x32_bf16 v[208:211], v[130:133], v[102:105], v[16:19]
	s_nop 2
	ds_read_b128 v[16:19], v202 offset:32768
	ds_read_b128 v[28:31], v202 offset:34816
	ds_read_b128 v[212:215], v60 offset:2048
	ds_read_b128 v[40:43], v202 offset:36864
	ds_read_b128 v[44:47], v202 offset:38912
	v_mfma_f32_16x16x32_bf16 v[36:39], v[118:121], v[98:101], v[36:39]
	v_mfma_f32_16x16x32_bf16 v[32:35], v[118:121], v[102:105], v[32:35]
	v_mfma_f32_16x16x32_bf16 v[20:23], v[130:133], v[98:101], v[20:23]
	s_waitcnt lgkmcnt(4)
	v_mfma_f32_16x16x32_bf16 v[148:151], v[24:27], v[16:19], v[146:149]
	s_waitcnt lgkmcnt(3)
	v_mfma_f32_16x16x32_bf16 v[132:135], v[24:27], v[28:31], v[142:145]
	s_waitcnt lgkmcnt(0)
	v_mfma_f32_16x16x32_bf16 v[100:103], v[24:27], v[44:47], v[198:201]
	v_mfma_f32_16x16x32_bf16 v[144:147], v[212:215], v[16:19], v[226:229]
	s_nop 1
	ds_read_b128 v[198:201], v60 offset:4096
	ds_read_b128 v[224:227], v60 offset:6144
	v_mfma_f32_16x16x32_bf16 v[116:119], v[24:27], v[40:43], v[138:141]
	v_mfma_f32_16x16x32_bf16 v[112:115], v[212:215], v[40:43], v[122:125]
	v_mfma_f32_16x16x32_bf16 v[96:99], v[212:215], v[44:47], v[230:233]
	s_waitcnt lgkmcnt(1)
	v_mfma_f32_16x16x32_bf16 v[108:111], v[198:201], v[40:43], v[106:109]
	s_waitcnt lgkmcnt(0)
	v_mfma_f32_16x16x32_bf16 v[136:139], v[224:227], v[16:19], v[168:171]
	v_mfma_f32_16x16x32_bf16 v[120:123], v[224:227], v[28:31], v[176:179]
	s_nop 1
	ds_read_b128 v[168:171], v202 offset:40960
	ds_read_b128 v[176:179], v202 offset:43008
	v_mfma_f32_16x16x32_bf16 v[104:107], v[224:227], v[40:43], v[190:193]
	s_nop 2
	ds_read_b128 v[190:193], v202 offset:45056
	ds_read_b128 v[228:231], v202 offset:47104
	s_waitcnt vmcnt(0)
	s_waitcnt lgkmcnt(0)
	v_mfma_f32_16x16x32_bf16 v[128:131], v[212:215], v[28:31], v[126:129]
	s_barrier
	v_mfma_f32_16x16x32_bf16 v[140:143], v[198:201], v[16:19], v[234:237]
	v_mfma_f32_16x16x32_bf16 v[124:127], v[198:201], v[28:31], v[238:241]
	v_mfma_f32_16x16x32_bf16 v[92:95], v[198:201], v[44:47], v[242:245]
	v_mfma_f32_16x16x32_bf16 v[88:91], v[224:227], v[44:47], v[86:89]
	v_mfma_f32_16x16x32_bf16 v[76:79], v[24:27], v[168:171], v[76:79]
	v_mfma_f32_16x16x32_bf16 v[60:63], v[24:27], v[176:179], v[72:75]
	v_mfma_f32_16x16x32_bf16 v[44:47], v[24:27], v[190:193], v[68:71]
	v_mfma_f32_16x16x32_bf16 v[28:31], v[24:27], v[228:231], v[64:67]
	v_mfma_f32_16x16x32_bf16 v[72:75], v[212:215], v[168:171], v[164:167]
	v_mfma_f32_16x16x32_bf16 v[56:59], v[212:215], v[176:179], v[56:59]
	v_mfma_f32_16x16x32_bf16 v[40:43], v[212:215], v[190:193], v[52:55]
	v_mfma_f32_16x16x32_bf16 v[24:27], v[212:215], v[228:231], v[48:51]
	v_mfma_f32_16x16x32_bf16 v[68:71], v[198:201], v[168:171], v[172:175]
	v_mfma_f32_16x16x32_bf16 v[52:55], v[198:201], v[176:179], v[194:197]
	v_mfma_f32_16x16x32_bf16 v[36:39], v[198:201], v[190:193], v[36:39]
	v_mfma_f32_16x16x32_bf16 v[16:19], v[198:201], v[228:231], v[32:35]
	v_mfma_f32_16x16x32_bf16 v[64:67], v[224:227], v[168:171], v[246:249]
	v_mfma_f32_16x16x32_bf16 v[48:51], v[224:227], v[176:179], v[182:185]
	v_mfma_f32_16x16x32_bf16 v[32:35], v[224:227], v[190:193], v[20:23]
	v_mfma_f32_16x16x32_bf16 v[20:23], v[224:227], v[228:231], v[208:211]
	s_cbranch_vccz .LBB0_565
	v_mov_b32_e32 v166, v188
	s_ashr_i32 s18, s79, 5
	v_ashrrev_i32_e32 v167, 3, v166
	v_lshrrev_b32_e32 v87, 1, v167
	s_ashr_i32 s19, s18, 31
	v_xor_b32_e32 v87, v87, v166
	s_lshl_b64 s[18:19], s[18:19], 19
	v_add_lshl_u32 v86, v167, s94, 10
	v_lshlrev_b32_e32 v87, 3, v87
	s_add_u32 s18, s57, s18
	v_and_or_b32 v86, v87, 56, v86
	s_addc_u32 s19, s93, s19
	s_lshl_b32 s0, s0, 19
	v_ashrrev_i32_e32 v87, 31, v86
	s_add_u32 s28, s85, s0
	v_lshlrev_b64 v[86:87], 1, v[86:87]
	s_mov_b32 m0, s96
	s_addc_u32 s29, s33, 0
	v_lshl_add_u64 v[164:165], s[18:19], 0, v[86:87]
	global_load_lds_dwordx4 v[164:165], off
	v_lshl_add_u64 v[86:87], s[28:29], 0, v[86:87]
	s_add_i32 m0, s96, 0x8000
	v_readlane_b32 s0, v255, 17
	global_load_lds_dwordx4 v[86:87], off
	s_nop 0
	v_add_u32_e32 v86, s0, v167
	v_lshlrev_b32_e32 v87, 10, v86
	v_lshrrev_b32_e32 v86, 1, v86
	v_xor_b32_e32 v86, v86, v166
	v_lshlrev_b32_e32 v86, 3, v86
	v_and_or_b32 v86, v86, 56, v87
	v_ashrrev_i32_e32 v87, 31, v86
	v_lshlrev_b64 v[86:87], 1, v[86:87]
	v_readlane_b32 s0, v255, 11
	v_lshl_add_u64 v[164:165], s[18:19], 0, v[86:87]
	s_mov_b32 m0, s0
	v_lshl_add_u64 v[86:87], s[28:29], 0, v[86:87]
	global_load_lds_dwordx4 v[164:165], off
	s_add_i32 m0, s0, 0x8000
	v_readlane_b32 s0, v255, 18
	global_load_lds_dwordx4 v[86:87], off
	s_nop 0
	v_add_u32_e32 v86, s0, v167
	v_lshlrev_b32_e32 v87, 10, v86
	v_lshrrev_b32_e32 v86, 1, v86
	v_xor_b32_e32 v86, v86, v166
	v_lshlrev_b32_e32 v86, 3, v86
	v_and_or_b32 v86, v86, 56, v87
	v_ashrrev_i32_e32 v87, 31, v86
	v_lshlrev_b64 v[86:87], 1, v[86:87]
	v_readlane_b32 s0, v254, 59
	v_lshl_add_u64 v[164:165], s[18:19], 0, v[86:87]
	s_mov_b32 m0, s0
	v_lshl_add_u64 v[86:87], s[28:29], 0, v[86:87]
	global_load_lds_dwordx4 v[164:165], off
	s_add_i32 m0, s0, 0x8000
	v_readlane_b32 s0, v254, 19
	global_load_lds_dwordx4 v[86:87], off
	s_nop 0
	v_add_u32_e32 v86, s0, v167
	v_lshlrev_b32_e32 v87, 10, v86
	v_lshrrev_b32_e32 v86, 1, v86
	v_xor_b32_e32 v86, v86, v166
	v_lshlrev_b32_e32 v86, 3, v86
	v_and_or_b32 v86, v86, 56, v87
	v_ashrrev_i32_e32 v87, 31, v86
	v_lshlrev_b64 v[86:87], 1, v[86:87]
	v_readlane_b32 s0, v254, 60
	v_lshl_add_u64 v[164:165], s[18:19], 0, v[86:87]
	s_mov_b32 m0, s0
	v_lshl_add_u64 v[86:87], s[28:29], 0, v[86:87]
	global_load_lds_dwordx4 v[164:165], off
	s_add_i32 m0, s0, 0x8000
	s_nop 0
	global_load_lds_dwordx4 v[86:87], off
